# QK-norm: column offset by compares/selects instead of an exec-branch nest; lane exchanges within 8-lane groups by DPP (quad_perm / row_half_mirror) instead of ds_bpermute round trips
# baseline (speedup 1.0000x reference)
; #define GAS __attribute__((address_space(1)))
; DI void phase_qknorm(const Ctx& C, bf16_t* Z, const float* qkg  , const float* ropec, const float* ropes) {
;     ...
;         for (int j = 0; j < 4; ++j) { const int it = min(it0 + j * NG, NIT - 1); const int row = it / 42, s = it % 42;
;             const int col = s < 8 ? Z_AQ + 64 * s : s < 10 ? Z_AK + 64 * (s - 8) : s < 18 ? Z_BQ + 64 * (s - 10) : s < 26 ? Z_BK + 64 * (s - 18) : s < 34 ? Z_DQ + 64 * (s - 26) : Z_DK + 64 * (s - 34);
;             pp[j] = Z + (size_t)row * ZW + col + 8 * t8; raw[j] = *(const GAS u32x4*)pp[j]; }
; #pragma unroll
;         for (int j = 0; j < 4; ++j) {
;             const int it = it0 + j * NG; const int itc = min(it, NIT - 1); const int row = itc / 42, s = itc % 42;
;             const int gi = s < 8 ? 0 : s < 10 ? 1 : s < 18 ? 2 : s < 26 ? 3 : s < 34 ? 4 : 5;
;             const bool rope = (gi != 2 && gi != 3), isq = !(gi & 1);
.LBB0_553:
	s_mov_b32 s4, 0x30c30c31
	v_mul_hi_i32 v2, v43, s4
	v_lshrrev_b32_e32 v3, 31, v2
	v_ashrrev_i32_e32 v2, 3, v2
	v_add_u32_e32 v44, v2, v3
	v_mul_lo_u32 v2, v44, 42
	v_sub_u32_e32 v28, v43, v2
	v_cmp_lt_i32_e32 vcc, 7, v28
	v_cmp_lt_u32_e64 s[68:69], 9, v28
	v_cmp_lt_u32_e64 s[70:71], 25, v28
	v_lshlrev_b32_e32 v2, 6, v28
	s_nop 0
	v_cndmask_b32_e64 v3, 0, 1, s[68:69]
	v_cndmask_b32_e64 v4, 0, 1, s[70:71]
	v_lshlrev_b32_e32 v3, 7, v3
	v_lshlrev_b32_e32 v4, 10, v4
	v_add3_u32 v2, v2, v3, v4
	v_mov_b64_e32 v[4:5], s[86:87]
	v_mad_i64_i32 v[4:5], s[4:5], v44, s53, v[4:5]
	v_ashrrev_i32_e32 v3, 31, v2
	v_lshl_add_u64 v[2:3], v[2:3], 1, v[4:5]
	v_lshl_add_u64 v[26:27], v[2:3], 0, v[0:1]
	s_waitcnt lgkmcnt(2)
	global_load_dwordx4 v[14:17], v[26:27], off
	v_add_u32_e32 v37, s26, v43
	v_min_i32_e32 v2, 0x5e7ff, v37
	s_mov_b32 s4, 0x30c30c31
	v_mul_hi_i32 v3, v2, s4
	v_lshrrev_b32_e32 v4, 31, v3
	v_ashrrev_i32_e32 v3, 3, v3
	v_add_u32_e32 v41, v3, v4
	v_mul_lo_u32 v3, v41, 42
	v_sub_u32_e32 v42, v2, v3
	v_cmp_lt_i32_e64 s[6:7], 7, v42
	v_cmp_lt_u32_e64 s[68:69], 9, v42
	v_cmp_lt_u32_e64 s[70:71], 25, v42
	v_lshlrev_b32_e32 v2, 6, v42
	s_nop 0
	v_cndmask_b32_e64 v3, 0, 1, s[68:69]
	v_cndmask_b32_e64 v4, 0, 1, s[70:71]
	v_lshlrev_b32_e32 v3, 7, v3
	v_lshlrev_b32_e32 v4, 10, v4
	v_add3_u32 v2, v2, v3, v4
	v_mov_b64_e32 v[4:5], s[86:87]
	v_mad_i64_i32 v[4:5], s[4:5], v41, s53, v[4:5]
	v_ashrrev_i32_e32 v3, 31, v2
	v_lshl_add_u64 v[2:3], v[2:3], 1, v[4:5]
	v_lshl_add_u64 v[24:25], v[2:3], 0, v[0:1]
	s_waitcnt lgkmcnt(0)
	global_load_dwordx4 v[10:13], v[24:25], off
	v_add_u32_e32 v2, s27, v43
	v_min_i32_e32 v2, 0x5e7ff, v2
	s_mov_b32 s4, 0x30c30c31
	v_mul_hi_i32 v3, v2, s4
	v_lshrrev_b32_e32 v4, 31, v3
	v_ashrrev_i32_e32 v3, 3, v3
	v_add_u32_e32 v39, v3, v4
	v_mul_lo_u32 v3, v39, 42
	v_sub_u32_e32 v40, v2, v3
	v_cmp_lt_i32_e64 s[4:5], 7, v40
	v_cmp_lt_u32_e64 s[68:69], 9, v40
	v_cmp_lt_u32_e64 s[70:71], 25, v40
	v_lshlrev_b32_e32 v2, 6, v40
	s_nop 0
	v_cndmask_b32_e64 v3, 0, 1, s[68:69]
	v_cndmask_b32_e64 v4, 0, 1, s[70:71]
	v_lshlrev_b32_e32 v3, 7, v3
	v_lshlrev_b32_e32 v4, 10, v4
	v_add3_u32 v2, v2, v3, v4
	v_mov_b64_e32 v[4:5], s[86:87]
	v_mad_i64_i32 v[4:5], s[8:9], v39, s53, v[4:5]
	v_ashrrev_i32_e32 v3, 31, v2
	v_lshl_add_u64 v[2:3], v[2:3], 1, v[4:5]
	v_lshl_add_u64 v[22:23], v[2:3], 0, v[0:1]
	global_load_dwordx4 v[6:9], v[22:23], off
	s_mul_i32 s8, s48, 0xc0
	v_add_u32_e32 v2, s8, v43
	v_min_i32_e32 v2, 0x5e7ff, v2
	s_mov_b32 s8, 0x30c30c31
	v_mul_hi_i32 v3, v2, s8
	v_lshrrev_b32_e32 v4, 31, v3
	v_ashrrev_i32_e32 v3, 3, v3
	v_add_u32_e32 v36, v3, v4
	v_mul_lo_u32 v3, v36, 42
	v_sub_u32_e32 v38, v2, v3
	v_cmp_lt_i32_e64 s[8:9], 7, v38
	v_cmp_lt_u32_e64 s[68:69], 9, v38
	v_cmp_lt_u32_e64 s[70:71], 25, v38
	v_lshlrev_b32_e32 v2, 6, v38
	s_nop 0
	v_cndmask_b32_e64 v3, 0, 1, s[68:69]
	v_cndmask_b32_e64 v4, 0, 1, s[70:71]
	v_lshlrev_b32_e32 v3, 7, v3
	v_lshlrev_b32_e32 v4, 10, v4
	v_add3_u32 v2, v2, v3, v4
	v_mov_b64_e32 v[4:5], s[86:87]
	v_mad_i64_i32 v[4:5], s[10:11], v36, s53, v[4:5]
	v_ashrrev_i32_e32 v3, 31, v2
	v_lshl_add_u64 v[2:3], v[2:3], 1, v[4:5]
	v_lshl_add_u64 v[20:21], v[2:3], 0, v[0:1]
	global_load_dwordx4 v[2:5], v[20:21], off
	v_mov_b32_e32 v45, 0
	s_and_saveexec_b64 s[10:11], vcc
	s_cbranch_execz .LBB0_621
	v_cmp_lt_u32_e32 vcc, 9, v28
	v_mov_b32_e32 v45, 1
	s_and_saveexec_b64 s[20:21], vcc
	v_cmp_gt_u32_e32 vcc, 34, v28
	s_nop 1
	v_cndmask_b32_e64 v29, 5, 4, vcc
	v_cmp_lt_u32_e32 vcc, 25, v28
	s_nop 1
	v_cndmask_b32_e32 v29, 3, v29, vcc
	v_cmp_lt_u32_e32 vcc, 17, v28
	s_nop 1
	v_cndmask_b32_e32 v45, 2, v29, vcc
	s_or_b64 exec, exec, s[20:21]
; #define GAS __attribute__((address_space(1)))
; DI float bflo(unsigned u) { return __uint_as_float(u << 16); }
; DI float bfhi(unsigned u) { return __uint_as_float(u & 0xffff0000u); }
; DI float shx(float v, int m, int lane) { return __builtin_bit_cast(float, __builtin_amdgcn_ds_bpermute((lane ^ m) << 2, __builtin_bit_cast(int, v))); }
; DI void phase_qknorm(const Ctx& C, bf16_t* Z, const float* qkg  , const float* ropec, const float* ropes) {
;     ...
;             float x[8] = {bflo(rw.x), bfhi(rw.x), bflo(rw.y), bfhi(rw.y), bflo(rw.z), bfhi(rw.z), bflo(rw.w), bfhi(rw.w)};
;             float ss = 0.f;
; #pragma unroll
;             for (int i = 0; i < 8; ++i) ss += x[i] * x[i];
;             ss += shx(ss, 1, lane); ss += shx(ss, 2, lane); ss += shx(ss, 4, lane);
;             const float rstd = 1.f / sqrtf(ss * (1.f / 64.f) + EPS);
;             const f32x4 g0 = *(const GAS f32x4*)(qkg + gi * 64 + 8 * t8), g1 = *(const GAS f32x4*)(qkg + gi * 64 + 8 * t8 + 4);
;             x[0] *= rstd * g0.x; x[1] *= rstd * g0.y; x[2] *= rstd * g0.z; x[3] *= rstd * g0.w; x[4] *= rstd * g1.x; x[5] *= rstd * g1.y; x[6] *= rstd * g1.z; x[7] *= rstd * g1.w;
;             float px[8];
; #pragma unroll
;             for (int i = 0; i < 8; ++i) px[i] = shx(x[i], 2, lane);
;             if (rope && row < NLAT) {
;                 const int tok = row & (SEQ - 1), ab = tok * 32 + (t8 & 1) * 8 + (t8 >> 2) * 16;
;                 const f32x4 c0 = *(const GAS f32x4*)(ropec + ab), c1 = *(const GAS f32x4*)(ropec + ab + 4), s0 = *(const GAS f32x4*)(ropes + ab), s1 = *(const GAS f32x4*)(ropes + ab + 4);
;                 const float cc[8] = {c0.x, c0.y, c0.z, c0.w, c1.x, c1.y, c1.z, c1.w}, sn[8] = {s0.x, s0.y, s0.z, s0.w, s1.x, s1.y, s1.z, s1.w};
;                 const float sg = (t8 & 2) ? 1.f : -1.f;
; #pragma unroll
;                 for (int i = 0; i < 8; ++i) x[i] = x[i] * cc[i] + sg * px[i] * sn[i];
;             }
.LBB0_621:
	s_or_b64 exec, exec, s[10:11]
	v_lshlrev_b32_e32 v28, 8, v45
	v_mov_b32_e32 v29, v1
	v_lshl_add_u64 v[46:47], v[18:19], 0, v[28:29]
	global_load_dwordx4 v[28:31], v[46:47], off
	s_nop 0
	global_load_dwordx4 v[46:49], v[46:47], off offset:16
	s_waitcnt vmcnt(5)
	v_lshlrev_b32_e32 v52, 16, v14
	v_and_b32_e32 v53, 0xffff0000, v14
	v_and_b32_e32 v50, 0xffff0000, v17
	v_lshlrev_b32_e32 v51, 16, v17
	v_lshlrev_b32_e32 v54, 16, v15
	v_and_b32_e32 v55, 0xffff0000, v15
	v_lshlrev_b32_e32 v56, 16, v16
	v_and_b32_e32 v57, 0xffff0000, v16
	v_pk_mul_f32 v[16:17], v[52:53], v[52:53]
	v_pk_mul_f32 v[58:59], v[54:55], v[54:55]
	v_add_f32_e32 v16, v16, v17
	v_add_f32_e32 v16, v58, v16
	v_pk_mul_f32 v[60:61], v[56:57], v[56:57]
	v_add_f32_e32 v16, v59, v16
	v_add_f32_e32 v16, v60, v16
	v_pk_mul_f32 v[14:15], v[50:51], v[50:51]
	v_add_f32_e32 v16, v61, v16
	v_add_f32_e32 v15, v15, v16
	v_add_f32_e32 v14, v14, v15
	s_nop 1
	v_add_f32_dpp v14, v14, v14 quad_perm:[1,0,3,2] row_mask:0xf bank_mask:0xf
	s_nop 1
	v_add_f32_dpp v14, v14, v14 quad_perm:[2,3,0,1] row_mask:0xf bank_mask:0xf
	s_nop 1
	v_add_f32_dpp v14, v14, v14 row_half_mirror row_mask:0xf bank_mask:0xf
	v_fmamk_f32 v14, v14, 0x3c800000, v227
	v_mul_f32_e32 v15, 0x4f800000, v14
	v_cmp_gt_f32_e32 vcc, s67, v14
	s_nop 1
	v_cndmask_b32_e32 v14, v14, v15, vcc
	v_sqrt_f32_e32 v15, v14
	s_nop 0
	v_add_u32_e32 v16, -1, v15
	v_add_u32_e32 v17, 1, v15
	v_fma_f32 v58, -v16, v15, v14
	v_fma_f32 v59, -v17, v15, v14
	v_cmp_ge_f32_e64 s[10:11], 0, v58
	s_nop 1
	v_cndmask_b32_e64 v15, v15, v16, s[10:11]
	v_cmp_lt_f32_e64 s[10:11], 0, v59
	s_nop 1
	v_cndmask_b32_e64 v15, v15, v17, s[10:11]
	v_mul_f32_e32 v16, 0x37800000, v15
	v_cndmask_b32_e32 v15, v15, v16, vcc
	v_cmp_class_f32_e32 vcc, v14, v228
	s_nop 1
	v_cndmask_b32_e32 v14, v15, v14, vcc
	v_div_scale_f32 v15, s[10:11], v14, v14, 1.0
	v_rcp_f32_e32 v16, v15
	v_div_scale_f32 v17, vcc, 1.0, v14, 1.0
	v_cmp_gt_i32_e64 s[10:11], s59, v43
	v_fma_f32 v58, -v15, v16, 1.0
	v_fmac_f32_e32 v16, v58, v16
	v_mul_f32_e32 v58, v17, v16
	v_fma_f32 v59, -v15, v58, v17
	v_fmac_f32_e32 v58, v59, v16
	v_fma_f32 v15, -v15, v58, v17
	v_div_fmas_f32 v15, v15, v16, v58
	v_div_fixup_f32 v14, v15, v14, 1.0
	s_waitcnt vmcnt(1)
	v_pk_mul_f32 v[16:17], v[28:29], v[14:15] op_sel_hi:[1,0]
	v_pk_mul_f32 v[28:29], v[30:31], v[14:15] op_sel_hi:[1,0]
	s_waitcnt vmcnt(0)
	v_pk_mul_f32 v[30:31], v[46:47], v[14:15] op_sel_hi:[1,0]
	v_pk_mul_f32 v[46:47], v[48:49], v[14:15] op_sel_hi:[1,0]
	v_pk_mul_f32 v[14:15], v[16:17], v[52:53]
	v_pk_mul_f32 v[16:17], v[28:29], v[54:55]
	v_pk_mul_f32 v[28:29], v[30:31], v[56:57]
	v_pk_mul_f32 v[30:31], v[46:47], v[50:51] op_sel:[0,1] op_sel_hi:[1,0]
	s_nop 1
	v_mov_b32_dpp v52, v14 quad_perm:[2,3,0,1] row_mask:0xf bank_mask:0xf
	v_mov_b32_dpp v53, v15 quad_perm:[2,3,0,1] row_mask:0xf bank_mask:0xf
	v_mov_b32_dpp v50, v16 quad_perm:[2,3,0,1] row_mask:0xf bank_mask:0xf
	v_mov_b32_dpp v51, v17 quad_perm:[2,3,0,1] row_mask:0xf bank_mask:0xf
	v_mov_b32_dpp v48, v28 quad_perm:[2,3,0,1] row_mask:0xf bank_mask:0xf
	v_mov_b32_dpp v49, v29 quad_perm:[2,3,0,1] row_mask:0xf bank_mask:0xf
	v_mov_b32_dpp v47, v30 quad_perm:[2,3,0,1] row_mask:0xf bank_mask:0xf
	v_mov_b32_dpp v46, v31 quad_perm:[2,3,0,1] row_mask:0xf bank_mask:0xf
	v_add_u32_e32 v54, -4, v45
	v_cmp_gt_u32_e32 vcc, -2, v54
	s_and_b64 s[20:21], s[10:11], vcc
	s_and_saveexec_b64 s[10:11], s[20:21]
	s_cbranch_execz .LBB0_623
	v_lshlrev_b32_e32 v43, 5, v44
	s_mov_b32 s20, 0xffe0
	v_and_or_b32 v43, v43, s20, v35
	v_lshlrev_b32_e32 v43, 2, v43
	global_load_dwordx4 v[54:57], v43, s[14:15] offset:16
	global_load_dwordx4 v[58:61], v43, s[14:15]
	global_load_dwordx4 v[62:65], v43, s[16:17] offset:16
	global_load_dwordx4 v[66:69], v43, s[16:17]
	s_waitcnt lgkmcnt(1)
	v_cndmask_b32_e64 v43, v47, -v47, s[0:1]
	s_waitcnt lgkmcnt(0)
	v_cndmask_b32_e64 v47, v46, -v46, s[0:1]
	v_mov_b32_e32 v46, v31
	v_cndmask_b32_e64 v52, v52, -v52, s[0:1]
	v_cndmask_b32_e64 v53, v53, -v53, s[0:1]
	v_cndmask_b32_e64 v50, v50, -v50, s[0:1]
	v_cndmask_b32_e64 v51, v51, -v51, s[0:1]
	v_cndmask_b32_e64 v48, v48, -v48, s[0:1]
	v_cndmask_b32_e64 v49, v49, -v49, s[0:1]
	s_waitcnt vmcnt(3)
	v_mul_f32_e32 v30, v30, v56
	s_waitcnt vmcnt(1)
	v_mul_f32_e32 v56, v43, v64
	v_mov_b32_e32 v64, v57
	v_pk_mul_f32 v[46:47], v[46:47], v[64:65]
	s_waitcnt vmcnt(0)
	v_pk_mul_f32 v[52:53], v[52:53], v[66:67]
	v_pk_mul_f32 v[50:51], v[50:51], v[68:69]
	v_pk_mul_f32 v[48:49], v[48:49], v[62:63]
	v_mov_b32_e32 v31, v46
	v_mov_b32_e32 v57, v47
	v_pk_fma_f32 v[14:15], v[14:15], v[58:59], v[52:53]
	v_pk_fma_f32 v[16:17], v[16:17], v[60:61], v[50:51]
	v_pk_fma_f32 v[28:29], v[28:29], v[54:55], v[48:49]
	v_pk_add_f32 v[30:31], v[30:31], v[56:57]

; #define GAS __attribute__((address_space(1)))
; DI float bflo(unsigned u) { return __uint_as_float(u << 16); }
; DI float bfhi(unsigned u) { return __uint_as_float(u & 0xffff0000u); }
; DI float shx(float v, int m, int lane) { return __builtin_bit_cast(float, __builtin_amdgcn_ds_bpermute((lane ^ m) << 2, __builtin_bit_cast(int, v))); }
; DI void phase_qknorm(const Ctx& C, bf16_t* Z, const float* qkg  , const float* ropec, const float* ropes) {
;     ...
;             float x[8] = {bflo(rw.x), bfhi(rw.x), bflo(rw.y), bfhi(rw.y), bflo(rw.z), bfhi(rw.z), bflo(rw.w), bfhi(rw.w)};
;             float ss = 0.f;
; #pragma unroll
;             for (int i = 0; i < 8; ++i) ss += x[i] * x[i];
;             ss += shx(ss, 1, lane); ss += shx(ss, 2, lane); ss += shx(ss, 4, lane);
;             const float rstd = 1.f / sqrtf(ss * (1.f / 64.f) + EPS);
;             const f32x4 g0 = *(const GAS f32x4*)(qkg + gi * 64 + 8 * t8), g1 = *(const GAS f32x4*)(qkg + gi * 64 + 8 * t8 + 4);
;             x[0] *= rstd * g0.x; x[1] *= rstd * g0.y; x[2] *= rstd * g0.z; x[3] *= rstd * g0.w; x[4] *= rstd * g1.x; x[5] *= rstd * g1.y; x[6] *= rstd * g1.z; x[7] *= rstd * g1.w;
;             float px[8];
; #pragma unroll
;             for (int i = 0; i < 8; ++i) px[i] = shx(x[i], 2, lane);
;             if (rope && row < NLAT) {
;                 const int tok = row & (SEQ - 1), ab = tok * 32 + (t8 & 1) * 8 + (t8 >> 2) * 16;
;                 const f32x4 c0 = *(const GAS f32x4*)(ropec + ab), c1 = *(const GAS f32x4*)(ropec + ab + 4), s0 = *(const GAS f32x4*)(ropes + ab), s1 = *(const GAS f32x4*)(ropes + ab + 4);
;                 const float cc[8] = {c0.x, c0.y, c0.z, c0.w, c1.x, c1.y, c1.z, c1.w}, sn[8] = {s0.x, s0.y, s0.z, s0.w, s1.x, s1.y, s1.z, s1.w};
;                 const float sg = (t8 & 2) ? 1.f : -1.f;
; #pragma unroll
;                 for (int i = 0; i < 8; ++i) x[i] = x[i] * cc[i] + sg * px[i] * sn[i];
;             }
.LBB0_627:
	s_or_b64 exec, exec, s[10:11]
	v_lshlrev_b32_e32 v14, 8, v43
	v_mov_b32_e32 v15, v1
	v_lshl_add_u64 v[26:27], v[18:19], 0, v[14:15]
	global_load_dwordx4 v[14:17], v[26:27], off
	s_nop 0
	global_load_dwordx4 v[26:29], v[26:27], off offset:16
	v_lshlrev_b32_e32 v44, 16, v10
	v_and_b32_e32 v45, 0xffff0000, v10
	v_and_b32_e32 v30, 0xffff0000, v13
	v_lshlrev_b32_e32 v31, 16, v13
	v_lshlrev_b32_e32 v46, 16, v11
	v_and_b32_e32 v47, 0xffff0000, v11
	v_lshlrev_b32_e32 v48, 16, v12
	v_and_b32_e32 v49, 0xffff0000, v12
	v_pk_mul_f32 v[12:13], v[44:45], v[44:45]
	v_pk_mul_f32 v[50:51], v[46:47], v[46:47]
	v_add_f32_e32 v12, v12, v13
	v_add_f32_e32 v12, v50, v12
	v_pk_mul_f32 v[52:53], v[48:49], v[48:49]
	v_add_f32_e32 v12, v51, v12
	v_add_f32_e32 v12, v52, v12
	v_pk_mul_f32 v[10:11], v[30:31], v[30:31]
	v_add_f32_e32 v12, v53, v12
	v_add_f32_e32 v11, v11, v12
	v_add_f32_e32 v10, v10, v11
	s_nop 1
	v_add_f32_dpp v10, v10, v10 quad_perm:[1,0,3,2] row_mask:0xf bank_mask:0xf
	s_nop 1
	v_add_f32_dpp v10, v10, v10 quad_perm:[2,3,0,1] row_mask:0xf bank_mask:0xf
	s_nop 1
	v_add_f32_dpp v10, v10, v10 row_half_mirror row_mask:0xf bank_mask:0xf
	v_fmamk_f32 v10, v10, 0x3c800000, v227
	v_mul_f32_e32 v11, 0x4f800000, v10
	v_cmp_gt_f32_e32 vcc, s67, v10
	s_nop 1
	v_cndmask_b32_e32 v10, v10, v11, vcc
	v_sqrt_f32_e32 v11, v10
	s_nop 0
	v_add_u32_e32 v12, -1, v11
	v_add_u32_e32 v13, 1, v11
	v_fma_f32 v42, -v12, v11, v10
	v_fma_f32 v50, -v13, v11, v10
	v_cmp_ge_f32_e64 s[6:7], 0, v42
	s_nop 1
	v_cndmask_b32_e64 v11, v11, v12, s[6:7]
	v_cmp_lt_f32_e64 s[6:7], 0, v50
	s_nop 1
	v_cndmask_b32_e64 v11, v11, v13, s[6:7]
	v_mul_f32_e32 v12, 0x37800000, v11
	v_cndmask_b32_e32 v11, v11, v12, vcc
	v_cmp_class_f32_e32 vcc, v10, v228
	s_nop 1
	v_cndmask_b32_e32 v10, v11, v10, vcc
	v_div_scale_f32 v11, s[6:7], v10, v10, 1.0
	v_rcp_f32_e32 v12, v11
	v_div_scale_f32 v13, vcc, 1.0, v10, 1.0
	v_cmp_gt_i32_e64 s[6:7], s59, v37
	v_fma_f32 v42, -v11, v12, 1.0
	v_fmac_f32_e32 v12, v42, v12
	v_mul_f32_e32 v42, v13, v12
	v_fma_f32 v50, -v11, v42, v13
	v_fmac_f32_e32 v42, v50, v12
	v_fma_f32 v11, -v11, v42, v13
	v_div_fmas_f32 v11, v11, v12, v42
	v_div_fixup_f32 v10, v11, v10, 1.0
	s_waitcnt vmcnt(1)
	v_pk_mul_f32 v[12:13], v[14:15], v[10:11] op_sel_hi:[1,0]
	v_pk_mul_f32 v[14:15], v[16:17], v[10:11] op_sel_hi:[1,0]
	s_waitcnt vmcnt(0)
	v_pk_mul_f32 v[16:17], v[26:27], v[10:11] op_sel_hi:[1,0]
	v_pk_mul_f32 v[26:27], v[28:29], v[10:11] op_sel_hi:[1,0]
	v_pk_mul_f32 v[10:11], v[12:13], v[44:45]
	v_pk_mul_f32 v[12:13], v[14:15], v[46:47]
	v_pk_mul_f32 v[14:15], v[16:17], v[48:49]
	v_pk_mul_f32 v[16:17], v[26:27], v[30:31] op_sel:[0,1] op_sel_hi:[1,0]
	s_nop 1
	v_mov_b32_dpp v42, v10 quad_perm:[2,3,0,1] row_mask:0xf bank_mask:0xf
	v_mov_b32_dpp v44, v11 quad_perm:[2,3,0,1] row_mask:0xf bank_mask:0xf
	v_mov_b32_dpp v30, v12 quad_perm:[2,3,0,1] row_mask:0xf bank_mask:0xf
	v_mov_b32_dpp v31, v13 quad_perm:[2,3,0,1] row_mask:0xf bank_mask:0xf
	v_mov_b32_dpp v28, v14 quad_perm:[2,3,0,1] row_mask:0xf bank_mask:0xf
	v_mov_b32_dpp v29, v15 quad_perm:[2,3,0,1] row_mask:0xf bank_mask:0xf
	v_mov_b32_dpp v27, v16 quad_perm:[2,3,0,1] row_mask:0xf bank_mask:0xf
	v_mov_b32_dpp v26, v17 quad_perm:[2,3,0,1] row_mask:0xf bank_mask:0xf
	v_add_u32_e32 v45, -4, v43
	v_cmp_gt_u32_e32 vcc, -2, v45
	s_and_b64 s[10:11], s[6:7], vcc
	s_and_saveexec_b64 s[6:7], s[10:11]
	s_cbranch_execz .LBB0_630
	v_lshlrev_b32_e32 v41, 5, v41
	s_mov_b32 s10, 0xffe0
	v_and_or_b32 v41, v41, s10, v35
	v_lshlrev_b32_e32 v41, 2, v41
	global_load_dwordx4 v[46:49], v41, s[14:15] offset:16
	global_load_dwordx4 v[50:53], v41, s[14:15]
	global_load_dwordx4 v[54:57], v41, s[16:17] offset:16
	global_load_dwordx4 v[58:61], v41, s[16:17]
	s_waitcnt lgkmcnt(1)
	v_cndmask_b32_e64 v27, v27, -v27, s[0:1]
	v_cndmask_b32_e64 v62, v42, -v42, s[0:1]
	v_cndmask_b32_e64 v63, v44, -v44, s[0:1]
	v_cndmask_b32_e64 v30, v30, -v30, s[0:1]
	v_cndmask_b32_e64 v31, v31, -v31, s[0:1]
	v_cndmask_b32_e64 v28, v28, -v28, s[0:1]
	v_cndmask_b32_e64 v29, v29, -v29, s[0:1]
	s_waitcnt vmcnt(3)
	v_mul_f32_e32 v16, v16, v48
	s_waitcnt vmcnt(1)
	v_mul_f32_e32 v48, v27, v56
	s_waitcnt lgkmcnt(0)
	v_cndmask_b32_e64 v27, v26, -v26, s[0:1]
	v_mov_b32_e32 v26, v17
	v_mov_b32_e32 v56, v49
	v_pk_mul_f32 v[26:27], v[26:27], v[56:57]
	s_waitcnt vmcnt(0)
	v_pk_mul_f32 v[44:45], v[62:63], v[58:59]
	v_pk_mul_f32 v[30:31], v[30:31], v[60:61]
	v_pk_mul_f32 v[28:29], v[28:29], v[54:55]
	v_mov_b32_e32 v17, v26
	v_mov_b32_e32 v49, v27
	v_pk_fma_f32 v[10:11], v[10:11], v[50:51], v[44:45]
	v_pk_fma_f32 v[12:13], v[12:13], v[52:53], v[30:31]
	v_pk_fma_f32 v[14:15], v[14:15], v[46:47], v[28:29]
	v_pk_add_f32 v[16:17], v[16:17], v[48:49]
	s_or_b64 exec, exec, s[6:7]
	v_cmp_gt_i32_e32 vcc, s90, v37
	s_and_saveexec_b64 s[6:7], vcc
	s_cbranch_execnz .LBB0_631

; #define GAS __attribute__((address_space(1)))
; DI float bflo(unsigned u) { return __uint_as_float(u << 16); }
; DI float bfhi(unsigned u) { return __uint_as_float(u & 0xffff0000u); }
; DI float shx(float v, int m, int lane) { return __builtin_bit_cast(float, __builtin_amdgcn_ds_bpermute((lane ^ m) << 2, __builtin_bit_cast(int, v))); }
; DI void phase_qknorm(const Ctx& C, bf16_t* Z, const float* qkg  , const float* ropec, const float* ropes) {
;     ...
;             float x[8] = {bflo(rw.x), bfhi(rw.x), bflo(rw.y), bfhi(rw.y), bflo(rw.z), bfhi(rw.z), bflo(rw.w), bfhi(rw.w)};
;             float ss = 0.f;
; #pragma unroll
;             for (int i = 0; i < 8; ++i) ss += x[i] * x[i];
;             ss += shx(ss, 1, lane); ss += shx(ss, 2, lane); ss += shx(ss, 4, lane);
;             const float rstd = 1.f / sqrtf(ss * (1.f / 64.f) + EPS);
;             const f32x4 g0 = *(const GAS f32x4*)(qkg + gi * 64 + 8 * t8), g1 = *(const GAS f32x4*)(qkg + gi * 64 + 8 * t8 + 4);
;             x[0] *= rstd * g0.x; x[1] *= rstd * g0.y; x[2] *= rstd * g0.z; x[3] *= rstd * g0.w; x[4] *= rstd * g1.x; x[5] *= rstd * g1.y; x[6] *= rstd * g1.z; x[7] *= rstd * g1.w;
;             float px[8];
; #pragma unroll
;             for (int i = 0; i < 8; ++i) px[i] = shx(x[i], 2, lane);
;             if (rope && row < NLAT) {
;                 const int tok = row & (SEQ - 1), ab = tok * 32 + (t8 & 1) * 8 + (t8 >> 2) * 16;
;                 const f32x4 c0 = *(const GAS f32x4*)(ropec + ab), c1 = *(const GAS f32x4*)(ropec + ab + 4), s0 = *(const GAS f32x4*)(ropes + ab), s1 = *(const GAS f32x4*)(ropes + ab + 4);
;                 const float cc[8] = {c0.x, c0.y, c0.z, c0.w, c1.x, c1.y, c1.z, c1.w}, sn[8] = {s0.x, s0.y, s0.z, s0.w, s1.x, s1.y, s1.z, s1.w};
;                 const float sg = (t8 & 2) ? 1.f : -1.f;
; #pragma unroll
;                 for (int i = 0; i < 8; ++i) x[i] = x[i] * cc[i] + sg * px[i] * sn[i];
;             }
.LBB0_635:
	s_or_b64 exec, exec, s[6:7]
	v_lshlrev_b32_e32 v10, 8, v15
	v_mov_b32_e32 v11, v1
	v_lshl_add_u64 v[16:17], v[18:19], 0, v[10:11]
	global_load_dwordx4 v[10:13], v[16:17], off
	s_waitcnt lgkmcnt(0)
	global_load_dwordx4 v[24:27], v[16:17], off offset:16
	v_lshlrev_b32_e32 v28, 16, v6
	v_and_b32_e32 v29, 0xffff0000, v6
	v_and_b32_e32 v16, 0xffff0000, v9
	v_lshlrev_b32_e32 v17, 16, v9
	v_lshlrev_b32_e32 v30, 16, v7
	v_and_b32_e32 v31, 0xffff0000, v7
	v_lshlrev_b32_e32 v40, 16, v8
	v_and_b32_e32 v41, 0xffff0000, v8
	v_pk_mul_f32 v[8:9], v[28:29], v[28:29]
	v_pk_mul_f32 v[42:43], v[30:31], v[30:31]
	v_add_f32_e32 v8, v8, v9
	v_add_f32_e32 v8, v42, v8
	v_pk_mul_f32 v[44:45], v[40:41], v[40:41]
	v_add_f32_e32 v8, v43, v8
	v_add_f32_e32 v8, v44, v8
	v_pk_mul_f32 v[6:7], v[16:17], v[16:17]
	v_add_f32_e32 v8, v45, v8
	v_add_f32_e32 v7, v7, v8
	v_add_f32_e32 v6, v6, v7
	s_nop 1
	v_add_f32_dpp v6, v6, v6 quad_perm:[1,0,3,2] row_mask:0xf bank_mask:0xf
	s_nop 1
	v_add_f32_dpp v6, v6, v6 quad_perm:[2,3,0,1] row_mask:0xf bank_mask:0xf
	s_nop 1
	v_add_f32_dpp v6, v6, v6 row_half_mirror row_mask:0xf bank_mask:0xf
	v_fmamk_f32 v6, v6, 0x3c800000, v227
	v_mul_f32_e32 v7, 0x4f800000, v6
	v_cmp_gt_f32_e32 vcc, s67, v6
	s_nop 1
	v_cndmask_b32_e32 v6, v6, v7, vcc
	v_sqrt_f32_e32 v7, v6
	s_nop 0
	v_add_u32_e32 v8, -1, v7
	v_add_u32_e32 v9, 1, v7
	v_fma_f32 v14, -v8, v7, v6
	v_fma_f32 v42, -v9, v7, v6
	v_cmp_ge_f32_e64 s[4:5], 0, v14
	v_add_u32_e32 v14, -4, v15
	s_nop 0
	v_cndmask_b32_e64 v7, v7, v8, s[4:5]
	v_cmp_lt_f32_e64 s[4:5], 0, v42
	s_nop 1
	v_cndmask_b32_e64 v7, v7, v9, s[4:5]
	v_mul_f32_e32 v8, 0x37800000, v7
	v_cndmask_b32_e32 v7, v7, v8, vcc
	v_cmp_class_f32_e32 vcc, v6, v228
	s_nop 1
	v_cndmask_b32_e32 v6, v7, v6, vcc
	v_div_scale_f32 v7, s[4:5], v6, v6, 1.0
	v_rcp_f32_e32 v8, v7
	v_div_scale_f32 v9, vcc, 1.0, v6, 1.0
	v_fma_f32 v42, -v7, v8, 1.0
	v_fmac_f32_e32 v8, v42, v8
	v_mul_f32_e32 v42, v9, v8
	v_fma_f32 v43, -v7, v42, v9
	v_fmac_f32_e32 v42, v43, v8
	v_fma_f32 v7, -v7, v42, v9
	v_div_fmas_f32 v7, v7, v8, v42
	v_div_fixup_f32 v6, v7, v6, 1.0
	s_waitcnt vmcnt(1)
	v_pk_mul_f32 v[8:9], v[10:11], v[6:7] op_sel_hi:[1,0]
	v_pk_mul_f32 v[10:11], v[12:13], v[6:7] op_sel_hi:[1,0]
	s_waitcnt vmcnt(0)
	v_pk_mul_f32 v[12:13], v[24:25], v[6:7] op_sel_hi:[1,0]
	v_pk_mul_f32 v[24:25], v[26:27], v[6:7] op_sel_hi:[1,0]
	v_pk_mul_f32 v[6:7], v[8:9], v[28:29]
	v_pk_mul_f32 v[8:9], v[10:11], v[30:31]
	v_pk_mul_f32 v[10:11], v[12:13], v[40:41]
	v_pk_mul_f32 v[12:13], v[24:25], v[16:17] op_sel:[0,1] op_sel_hi:[1,0]
	s_nop 1
	v_mov_b32_dpp v28, v6 quad_perm:[2,3,0,1] row_mask:0xf bank_mask:0xf
	v_mov_b32_dpp v29, v7 quad_perm:[2,3,0,1] row_mask:0xf bank_mask:0xf
	v_mov_b32_dpp v26, v8 quad_perm:[2,3,0,1] row_mask:0xf bank_mask:0xf
	v_mov_b32_dpp v27, v9 quad_perm:[2,3,0,1] row_mask:0xf bank_mask:0xf
	v_mov_b32_dpp v24, v10 quad_perm:[2,3,0,1] row_mask:0xf bank_mask:0xf
	v_mov_b32_dpp v25, v11 quad_perm:[2,3,0,1] row_mask:0xf bank_mask:0xf
	v_mov_b32_dpp v17, v12 quad_perm:[2,3,0,1] row_mask:0xf bank_mask:0xf
	v_mov_b32_dpp v16, v13 quad_perm:[2,3,0,1] row_mask:0xf bank_mask:0xf
	v_cmp_gt_u32_e32 vcc, -2, v14
	v_add_u32_e32 v14, s26, v37
	v_cmp_gt_i32_e64 s[4:5], s59, v14
	s_and_b64 s[6:7], s[4:5], vcc
	s_and_saveexec_b64 s[4:5], s[6:7]
	s_cbranch_execz .LBB0_638
	v_lshlrev_b32_e32 v30, 5, v39
	s_mov_b32 s6, 0xffe0
	v_and_or_b32 v30, v30, s6, v35
	v_lshlrev_b32_e32 v30, 2, v30
	global_load_dwordx4 v[40:43], v30, s[14:15] offset:16
	global_load_dwordx4 v[44:47], v30, s[14:15]
	global_load_dwordx4 v[48:51], v30, s[16:17] offset:16
	global_load_dwordx4 v[52:55], v30, s[16:17]
	s_waitcnt lgkmcnt(1)
	v_cndmask_b32_e64 v17, v17, -v17, s[0:1]
	v_cndmask_b32_e64 v28, v28, -v28, s[0:1]
	v_cndmask_b32_e64 v29, v29, -v29, s[0:1]
	v_cndmask_b32_e64 v26, v26, -v26, s[0:1]
	v_cndmask_b32_e64 v27, v27, -v27, s[0:1]
	v_cndmask_b32_e64 v24, v24, -v24, s[0:1]
	v_cndmask_b32_e64 v25, v25, -v25, s[0:1]
	s_waitcnt vmcnt(3)
	v_mul_f32_e32 v12, v12, v42
	s_waitcnt vmcnt(1)
	v_mul_f32_e32 v30, v17, v50
	s_waitcnt lgkmcnt(0)
	v_cndmask_b32_e64 v17, v16, -v16, s[0:1]
	v_mov_b32_e32 v16, v13
	v_mov_b32_e32 v50, v43
	v_pk_mul_f32 v[16:17], v[16:17], v[50:51]
	s_waitcnt vmcnt(0)
	v_pk_mul_f32 v[28:29], v[28:29], v[52:53]
	v_pk_mul_f32 v[26:27], v[26:27], v[54:55]
	v_pk_mul_f32 v[24:25], v[24:25], v[48:49]
	v_mov_b32_e32 v13, v16
	v_mov_b32_e32 v31, v17
	v_pk_fma_f32 v[6:7], v[6:7], v[44:45], v[28:29]
	v_pk_fma_f32 v[8:9], v[8:9], v[46:47], v[26:27]
	v_pk_fma_f32 v[10:11], v[10:11], v[40:41], v[24:25]
	v_pk_add_f32 v[12:13], v[12:13], v[30:31]
	s_or_b64 exec, exec, s[4:5]
	v_cmp_gt_i32_e32 vcc, s90, v14
	s_and_saveexec_b64 s[4:5], vcc
	s_cbranch_execnz .LBB0_639

; #define GAS __attribute__((address_space(1)))
; DI float bflo(unsigned u) { return __uint_as_float(u << 16); }
; DI float bfhi(unsigned u) { return __uint_as_float(u & 0xffff0000u); }
; DI float shx(float v, int m, int lane) { return __builtin_bit_cast(float, __builtin_amdgcn_ds_bpermute((lane ^ m) << 2, __builtin_bit_cast(int, v))); }
; DI void phase_qknorm(const Ctx& C, bf16_t* Z, const float* qkg  , const float* ropec, const float* ropes) {
;     ...
;             float x[8] = {bflo(rw.x), bfhi(rw.x), bflo(rw.y), bfhi(rw.y), bflo(rw.z), bfhi(rw.z), bflo(rw.w), bfhi(rw.w)};
;             float ss = 0.f;
; #pragma unroll
;             for (int i = 0; i < 8; ++i) ss += x[i] * x[i];
;             ss += shx(ss, 1, lane); ss += shx(ss, 2, lane); ss += shx(ss, 4, lane);
;             const float rstd = 1.f / sqrtf(ss * (1.f / 64.f) + EPS);
;             const f32x4 g0 = *(const GAS f32x4*)(qkg + gi * 64 + 8 * t8), g1 = *(const GAS f32x4*)(qkg + gi * 64 + 8 * t8 + 4);
;             x[0] *= rstd * g0.x; x[1] *= rstd * g0.y; x[2] *= rstd * g0.z; x[3] *= rstd * g0.w; x[4] *= rstd * g1.x; x[5] *= rstd * g1.y; x[6] *= rstd * g1.z; x[7] *= rstd * g1.w;
;             float px[8];
; #pragma unroll
;             for (int i = 0; i < 8; ++i) px[i] = shx(x[i], 2, lane);
;             if (rope && row < NLAT) {
;                 const int tok = row & (SEQ - 1), ab = tok * 32 + (t8 & 1) * 8 + (t8 >> 2) * 16;
;                 const f32x4 c0 = *(const GAS f32x4*)(ropec + ab), c1 = *(const GAS f32x4*)(ropec + ab + 4), s0 = *(const GAS f32x4*)(ropes + ab), s1 = *(const GAS f32x4*)(ropes + ab + 4);
;                 const float cc[8] = {c0.x, c0.y, c0.z, c0.w, c1.x, c1.y, c1.z, c1.w}, sn[8] = {s0.x, s0.y, s0.z, s0.w, s1.x, s1.y, s1.z, s1.w};
;                 const float sg = (t8 & 2) ? 1.f : -1.f;
; #pragma unroll
;                 for (int i = 0; i < 8; ++i) x[i] = x[i] * cc[i] + sg * px[i] * sn[i];
;             }
.LBB0_643:
	s_or_b64 exec, exec, s[4:5]
	v_lshlrev_b32_e32 v6, 8, v10
	v_mov_b32_e32 v7, v1
	v_lshl_add_u64 v[12:13], v[18:19], 0, v[6:7]
	global_load_dwordx4 v[6:9], v[12:13], off
	s_waitcnt lgkmcnt(2)
	global_load_dwordx4 v[22:25], v[12:13], off offset:16
	s_waitcnt lgkmcnt(0)
	v_lshlrev_b32_e32 v16, 16, v2
	v_and_b32_e32 v17, 0xffff0000, v2
	v_and_b32_e32 v12, 0xffff0000, v5
	v_lshlrev_b32_e32 v13, 16, v5
	v_lshlrev_b32_e32 v26, 16, v3
	v_and_b32_e32 v27, 0xffff0000, v3
	v_lshlrev_b32_e32 v28, 16, v4
	v_and_b32_e32 v29, 0xffff0000, v4
	v_pk_mul_f32 v[4:5], v[16:17], v[16:17]
	v_pk_mul_f32 v[30:31], v[26:27], v[26:27]
	v_add_f32_e32 v4, v4, v5
	v_add_f32_e32 v4, v30, v4
	v_pk_mul_f32 v[38:39], v[28:29], v[28:29]
	v_add_f32_e32 v4, v31, v4
	v_add_f32_e32 v4, v38, v4
	v_pk_mul_f32 v[2:3], v[12:13], v[12:13]
	v_add_f32_e32 v4, v39, v4
	v_add_f32_e32 v3, v3, v4
	v_add_f32_e32 v2, v2, v3
	s_nop 1
	v_add_f32_dpp v2, v2, v2 quad_perm:[1,0,3,2] row_mask:0xf bank_mask:0xf
	s_nop 1
	v_add_f32_dpp v2, v2, v2 quad_perm:[2,3,0,1] row_mask:0xf bank_mask:0xf
	s_nop 1
	v_add_f32_dpp v2, v2, v2 row_half_mirror row_mask:0xf bank_mask:0xf
	v_fmamk_f32 v2, v2, 0x3c800000, v227
	v_mul_f32_e32 v3, 0x4f800000, v2
	v_cmp_gt_f32_e32 vcc, s67, v2
	s_nop 1
	v_cndmask_b32_e32 v2, v2, v3, vcc
	v_sqrt_f32_e32 v3, v2
	s_nop 0
	v_add_u32_e32 v4, -1, v3
	v_add_u32_e32 v5, 1, v3
	v_fma_f32 v11, -v4, v3, v2
	v_fma_f32 v15, -v5, v3, v2
	v_cmp_ge_f32_e64 s[4:5], 0, v11
	v_add_u32_e32 v11, -4, v10
	s_nop 0
	v_cndmask_b32_e64 v3, v3, v4, s[4:5]
	v_cmp_lt_f32_e64 s[4:5], 0, v15
	s_nop 1
	v_cndmask_b32_e64 v3, v3, v5, s[4:5]
	v_mul_f32_e32 v4, 0x37800000, v3
	v_cndmask_b32_e32 v3, v3, v4, vcc
	v_cmp_class_f32_e32 vcc, v2, v228
	s_nop 1
	v_cndmask_b32_e32 v2, v3, v2, vcc
	v_div_scale_f32 v3, s[4:5], v2, v2, 1.0
	v_rcp_f32_e32 v4, v3
	v_div_scale_f32 v5, vcc, 1.0, v2, 1.0
	v_fma_f32 v15, -v3, v4, 1.0
	v_fmac_f32_e32 v4, v15, v4
	v_mul_f32_e32 v15, v5, v4
	v_fma_f32 v30, -v3, v15, v5
	v_fmac_f32_e32 v15, v30, v4
	v_fma_f32 v3, -v3, v15, v5
	v_div_fmas_f32 v3, v3, v4, v15
	v_div_fixup_f32 v2, v3, v2, 1.0
	s_waitcnt vmcnt(1)
	v_pk_mul_f32 v[4:5], v[6:7], v[2:3] op_sel_hi:[1,0]
	v_pk_mul_f32 v[6:7], v[8:9], v[2:3] op_sel_hi:[1,0]
	s_waitcnt vmcnt(0)
	v_pk_mul_f32 v[8:9], v[22:23], v[2:3] op_sel_hi:[1,0]
	v_pk_mul_f32 v[22:23], v[24:25], v[2:3] op_sel_hi:[1,0]
	v_pk_mul_f32 v[2:3], v[4:5], v[16:17]
	v_pk_mul_f32 v[4:5], v[6:7], v[26:27]
	v_pk_mul_f32 v[6:7], v[8:9], v[28:29]
	v_pk_mul_f32 v[8:9], v[22:23], v[12:13] op_sel:[0,1] op_sel_hi:[1,0]
	s_nop 1
	v_mov_b32_dpp v23, v2 quad_perm:[2,3,0,1] row_mask:0xf bank_mask:0xf
	v_mov_b32_dpp v24, v3 quad_perm:[2,3,0,1] row_mask:0xf bank_mask:0xf
	v_mov_b32_dpp v17, v4 quad_perm:[2,3,0,1] row_mask:0xf bank_mask:0xf
	v_mov_b32_dpp v22, v5 quad_perm:[2,3,0,1] row_mask:0xf bank_mask:0xf
	v_mov_b32_dpp v15, v6 quad_perm:[2,3,0,1] row_mask:0xf bank_mask:0xf
	v_mov_b32_dpp v16, v7 quad_perm:[2,3,0,1] row_mask:0xf bank_mask:0xf
	v_mov_b32_dpp v13, v8 quad_perm:[2,3,0,1] row_mask:0xf bank_mask:0xf
	v_mov_b32_dpp v12, v9 quad_perm:[2,3,0,1] row_mask:0xf bank_mask:0xf
	v_cmp_gt_u32_e32 vcc, -2, v11
	v_add_u32_e32 v11, s26, v14
	v_cmp_gt_i32_e64 s[4:5], s59, v11
	s_and_b64 s[6:7], s[4:5], vcc
	s_and_saveexec_b64 s[4:5], s[6:7]
	s_cbranch_execz .LBB0_645
	v_lshlrev_b32_e32 v14, 5, v36
	s_mov_b32 s6, 0xffe0
	v_and_or_b32 v14, v14, s6, v35
	v_lshlrev_b32_e32 v14, 2, v14
	global_load_dwordx4 v[26:29], v14, s[14:15] offset:16
	global_load_dwordx4 v[36:39], v14, s[14:15]
	global_load_dwordx4 v[40:43], v14, s[16:17] offset:16
	global_load_dwordx4 v[44:47], v14, s[16:17]
	s_waitcnt lgkmcnt(1)
	v_cndmask_b32_e64 v13, v13, -v13, s[0:1]
	v_cndmask_b32_e64 v30, v23, -v23, s[0:1]
	v_cndmask_b32_e64 v31, v24, -v24, s[0:1]
	v_cndmask_b32_e64 v14, v15, -v15, s[0:1]
	v_cndmask_b32_e64 v15, v16, -v16, s[0:1]
	s_waitcnt vmcnt(3)
	v_mul_f32_e32 v8, v8, v28
	s_waitcnt vmcnt(1)
	v_mul_f32_e32 v16, v13, v42
	s_waitcnt lgkmcnt(0)
	v_cndmask_b32_e64 v13, v12, -v12, s[0:1]
	v_mov_b32_e32 v12, v9
	v_mov_b32_e32 v42, v29
	s_waitcnt vmcnt(0)
	v_pk_mul_f32 v[24:25], v[30:31], v[44:45]
	v_cndmask_b32_e64 v30, v17, -v17, s[0:1]
	v_cndmask_b32_e64 v31, v22, -v22, s[0:1]
	v_pk_mul_f32 v[12:13], v[12:13], v[42:43]
	v_pk_mul_f32 v[22:23], v[30:31], v[46:47]
	v_pk_mul_f32 v[14:15], v[14:15], v[40:41]
	v_mov_b32_e32 v9, v12
	v_mov_b32_e32 v17, v13
	v_pk_fma_f32 v[2:3], v[2:3], v[36:37], v[24:25]
	v_pk_fma_f32 v[4:5], v[4:5], v[38:39], v[22:23]
	v_pk_fma_f32 v[6:7], v[6:7], v[26:27], v[14:15]
	v_pk_add_f32 v[8:9], v[8:9], v[16:17]
